# v48: v46 + out-proj K-loop LDS-DMA (phases 2-8) addressed as SGPR base + 32-bit VGPR offset (14 v_lshl_add_u64 and 3 v_mov per iteration removed)
# baseline (speedup 1.0000x reference)
; #define G_STAGE(bufoff, gbase, voff) do { _Pragma("unroll") for (int _i = 0; _i < 2; ++_i) \
;     __builtin_amdgcn_global_load_lds((const unsigned*)((const char*)(gbase) + (voff)[_i]), (LAS unsigned*)(lds + (bufoff) + ldsw + _i * 8192), 16, 0, 0); } while (0)
; #define G_LDA(dst, b, h) do { _Pragma("unroll") for (int m = 0; m < 4; ++m) _Pragma("unroll") for (int k = 0; k < 2; ++k) dst[m][k] = *(const LAS bf16x8*)(lds + G_SA(b, h) + aoff + m * 2048 + k * 1024); } while (0)
; #define G_LDB(dst, b, h) do { _Pragma("unroll") for (int n = 0; n < 2; ++n) _Pragma("unroll") for (int k = 0; k < 2; ++k) dst[n][k] = *(const LAS bf16x8*)(lds + G_SB(b, h) + boff + n * 2048 + k * 1024); } while (0)
; #define G_MMA(ai, bj, At, Bt) do { __builtin_amdgcn_s_setprio(1); _Pragma("unroll") for (int m = 0; m < 4; ++m) _Pragma("unroll") for (int n = 0; n < 2; ++n) _Pragma("unroll") for (int k = 0; k < 2; ++k) \
;     acc[ai][bj][m][n] = __builtin_amdgcn_mfma_f32_16x16x32_bf16(Bt[n][k], At[m][k], acc[ai][bj][m][n], 0, 0, 0); __builtin_amdgcn_s_setprio(0); } while (0)
; template <int GP> DI void gemm_phase(const Params& p, int l, int which, char* smem, int wv) {
;     ...
;     const char* nA = has_next ? (const char*)Aglob + (size_t)nmt * tstep + (size_t)nk0 * 2 : cA;
;     const char* nB = has_next ? (const char*)Wt + (size_t)nnt * tstep + (size_t)nk0 * 2 : cB;
;     const bool n32 = has_next ? ((!which) && (nnt < 4)) : c32;
;     for (int t = 0; t < cnk; t += 2) {
;       const bool last = (t == cnk - 2);
;       const char* a1 = cA + (size_t)(t + 1) * kstep;
;       const char* a2 = last ? nA : cA + (size_t)(t + 2) * kstep; const char* b2 = last ? nB : cB + (size_t)(t + 2) * kstep;
;       const char* a3 = a2 + kstep; const char* b3 = b2 + kstep;
;       if (last) {
; #pragma unroll
;         for (int i = 0; i < 2; ++i) { vb0[i] = voffB(i, 0, n32); vb1[i] = voffB(i, 1, n32); }
;       }
;       G_LDB(B0, 0, 0); G_SCHED; G_LDA(At, 0, 0); G_STAGE(G_SA(1, 1), a1 + hstep, voffA);
;       G_WAIT_L(8); G_BAR; G_WAIT_L(0); G_MMA(0, 0, At, B0); G_BAR; G_SCHED;
;       G_LDB(B1, 0, 1); G_STAGE(G_SB(0, 0), b2, vb0);
;       G_BAR; G_WAIT_L(0); G_MMA(0, 1, At, B1); G_BAR;
;       G_LDA(At, 0, 1); G_STAGE(G_SA(0, 0), a2, voffA);
;       G_BAR; G_WAIT_L(0); G_MMA(1, 0, At, B0); G_BAR; G_SCHED;
;       G_STAGE(G_SB(0, 1), b2, vb1);
;       G_WAIT_V(6); G_BAR; G_MMA(1, 1, At, B1); G_BAR;
.LBB0_149:
	v_add_u32_e32 v135, 0x10000, v166
	s_add_u32 s61, s8, s26
	ds_read_b128 v[168:171], v135
	ds_read_b128 v[172:175], v135 offset:1024
	ds_read_b128 v[176:179], v135 offset:2048
	ds_read_b128 v[180:183], v135 offset:3072
	s_addc_u32 s62, s9, s27
	s_and_b64 s[30:31], s[28:29], exec
	s_cselect_b32 s31, s11, s62
	s_cselect_b32 s30, s57, s61
	s_add_u32 s61, s6, s26
	s_addc_u32 s62, s7, s27
	s_and_b64 s[28:29], s[28:29], exec
	s_cselect_b32 s28, s59, s61
	s_cselect_b32 s29, s58, s62
	s_mov_b32 m0, s53
	v_lshl_add_u64 v[216:217], s[8:9], 0, v[162:163]
	ds_read_b128 v[184:187], v165
	ds_read_b128 v[188:191], v165 offset:1024
	ds_read_b128 v[192:195], v165 offset:2048
	ds_read_b128 v[196:199], v165 offset:3072
	ds_read_b128 v[200:203], v165 offset:4096
	ds_read_b128 v[204:207], v165 offset:5120
	ds_read_b128 v[208:211], v165 offset:6144
	ds_read_b128 v[212:215], v165 offset:7168
	global_load_lds_dwordx4 v[216:217], off
	v_lshl_add_u64 v[216:217], s[8:9], 0, v[160:161]
	s_mov_b32 m0, s54
	s_nop 0
	global_load_lds_dwordx4 v[216:217], off
	s_waitcnt lgkmcnt(8)
	s_barrier
	s_waitcnt lgkmcnt(0)
	v_mfma_f32_16x16x32_bf16 v[62:65], v[168:171], v[184:187], v[62:65]
	v_mfma_f32_16x16x32_bf16 v[58:61], v[176:179], v[184:187], v[58:61]
	v_mfma_f32_16x16x32_bf16 v[54:57], v[168:171], v[192:195], v[54:57]
	v_mfma_f32_16x16x32_bf16 v[50:53], v[176:179], v[192:195], v[50:53]
	v_mfma_f32_16x16x32_bf16 v[46:49], v[168:171], v[200:203], v[46:49]
	v_mfma_f32_16x16x32_bf16 v[42:45], v[176:179], v[200:203], v[42:45]
	v_mfma_f32_16x16x32_bf16 v[38:41], v[168:171], v[208:211], v[38:41]
	v_mfma_f32_16x16x32_bf16 v[34:37], v[176:179], v[208:211], v[34:37]
	v_mfma_f32_16x16x32_bf16 v[62:65], v[172:175], v[188:191], v[62:65]
	v_mfma_f32_16x16x32_bf16 v[58:61], v[180:183], v[188:191], v[58:61]
	v_mfma_f32_16x16x32_bf16 v[54:57], v[172:175], v[196:199], v[54:57]
	v_mfma_f32_16x16x32_bf16 v[50:53], v[180:183], v[196:199], v[50:53]
	v_mfma_f32_16x16x32_bf16 v[46:49], v[172:175], v[204:207], v[46:49]
	v_mfma_f32_16x16x32_bf16 v[42:45], v[180:183], v[204:207], v[42:45]
	v_mfma_f32_16x16x32_bf16 v[38:41], v[172:175], v[212:215], v[38:41]
	v_mfma_f32_16x16x32_bf16 v[34:37], v[180:183], v[212:215], v[34:37]
	s_barrier
	s_mov_b32 m0, s1
	v_add_u32_e32 v135, 0x14000, v166
	ds_read_b128 v[216:219], v135
	ds_read_b128 v[220:223], v135 offset:1024
	ds_read_b128 v[224:227], v135 offset:2048
	ds_read_b128 v[238:241], v135 offset:3072
	global_load_lds_dwordx4 v0, s[28:29]
	s_mov_b32 m0, s3
	s_nop 0
	global_load_lds_dwordx4 v136, s[28:29]
	s_barrier
	s_waitcnt lgkmcnt(0)
	s_waitcnt lgkmcnt(0)
	v_mfma_f32_16x16x32_bf16 v[30:33], v[216:219], v[184:187], v[30:33]
	v_mfma_f32_16x16x32_bf16 v[26:29], v[224:227], v[184:187], v[26:29]
	v_mfma_f32_16x16x32_bf16 v[22:25], v[216:219], v[192:195], v[22:25]
	v_mfma_f32_16x16x32_bf16 v[18:21], v[224:227], v[192:195], v[18:21]
	v_mfma_f32_16x16x32_bf16 v[14:17], v[216:219], v[200:203], v[14:17]
	v_mfma_f32_16x16x32_bf16 v[10:13], v[224:227], v[200:203], v[10:13]
	v_mfma_f32_16x16x32_bf16 v[6:9], v[216:219], v[208:211], v[6:9]
	v_mfma_f32_16x16x32_bf16 v[2:5], v[224:227], v[208:211], v[2:5]
	v_mfma_f32_16x16x32_bf16 v[30:33], v[220:223], v[188:191], v[30:33]
	v_mfma_f32_16x16x32_bf16 v[26:29], v[238:241], v[188:191], v[26:29]
	v_mfma_f32_16x16x32_bf16 v[22:25], v[220:223], v[196:199], v[22:25]
	v_mfma_f32_16x16x32_bf16 v[18:21], v[238:241], v[196:199], v[18:21]
	v_mfma_f32_16x16x32_bf16 v[14:17], v[220:223], v[204:207], v[14:17]
	v_mfma_f32_16x16x32_bf16 v[10:13], v[238:241], v[204:207], v[10:13]
	v_mfma_f32_16x16x32_bf16 v[6:9], v[220:223], v[212:215], v[6:9]
	v_mfma_f32_16x16x32_bf16 v[2:5], v[238:241], v[212:215], v[2:5]
	s_mov_b32 m0, s38
	s_barrier
	ds_read_b128 v[184:187], v165 offset:16384
	ds_read_b128 v[188:191], v165 offset:17408
	ds_read_b128 v[192:195], v165 offset:18432
	ds_read_b128 v[196:199], v165 offset:19456
	ds_read_b128 v[200:203], v165 offset:20480
	ds_read_b128 v[204:207], v165 offset:21504
	ds_read_b128 v[208:211], v165 offset:22528
	ds_read_b128 v[212:215], v165 offset:23552
	global_load_lds_dwordx4 v130, s[30:31]
	s_mov_b32 m0, s5
	s_nop 0
	global_load_lds_dwordx4 v132, s[30:31]
	s_barrier
	s_waitcnt lgkmcnt(0)
	v_mfma_f32_16x16x32_bf16 v[66:69], v[168:171], v[184:187], v[66:69]
	v_mfma_f32_16x16x32_bf16 v[70:73], v[176:179], v[184:187], v[70:73]
	v_mfma_f32_16x16x32_bf16 v[74:77], v[168:171], v[192:195], v[74:77]
	v_mfma_f32_16x16x32_bf16 v[78:81], v[176:179], v[192:195], v[78:81]
	v_mfma_f32_16x16x32_bf16 v[82:85], v[168:171], v[200:203], v[82:85]
	v_mfma_f32_16x16x32_bf16 v[86:89], v[176:179], v[200:203], v[86:89]
	v_mfma_f32_16x16x32_bf16 v[90:93], v[168:171], v[208:211], v[90:93]
	v_mfma_f32_16x16x32_bf16 v[98:101], v[176:179], v[208:211], v[98:101]
	v_mfma_f32_16x16x32_bf16 v[66:69], v[172:175], v[188:191], v[66:69]
	v_mfma_f32_16x16x32_bf16 v[70:73], v[180:183], v[188:191], v[70:73]
	v_mfma_f32_16x16x32_bf16 v[74:77], v[172:175], v[196:199], v[74:77]
	v_mfma_f32_16x16x32_bf16 v[78:81], v[180:183], v[196:199], v[78:81]
	v_mfma_f32_16x16x32_bf16 v[82:85], v[172:175], v[204:207], v[82:85]
	v_mfma_f32_16x16x32_bf16 v[86:89], v[180:183], v[204:207], v[86:89]
	v_mfma_f32_16x16x32_bf16 v[90:93], v[172:175], v[212:215], v[90:93]
	v_mfma_f32_16x16x32_bf16 v[98:101], v[180:183], v[212:215], v[98:101]
	s_barrier
	s_mov_b32 m0, s41
	s_nop 0
	global_load_lds_dwordx4 v134, s[28:29]
	s_mov_b32 m0, s42
	s_nop 0
	global_load_lds_dwordx4 v154, s[28:29]
	s_waitcnt vmcnt(6)
	s_barrier
; #define G_STAGE(bufoff, gbase, voff) do { _Pragma("unroll") for (int _i = 0; _i < 2; ++_i) \
;     __builtin_amdgcn_global_load_lds((const unsigned*)((const char*)(gbase) + (voff)[_i]), (LAS unsigned*)(lds + (bufoff) + ldsw + _i * 8192), 16, 0, 0); } while (0)
; #define G_LDA(dst, b, h) do { _Pragma("unroll") for (int m = 0; m < 4; ++m) _Pragma("unroll") for (int k = 0; k < 2; ++k) dst[m][k] = *(const LAS bf16x8*)(lds + G_SA(b, h) + aoff + m * 2048 + k * 1024); } while (0)
; #define G_LDB(dst, b, h) do { _Pragma("unroll") for (int n = 0; n < 2; ++n) _Pragma("unroll") for (int k = 0; k < 2; ++k) dst[n][k] = *(const LAS bf16x8*)(lds + G_SB(b, h) + boff + n * 2048 + k * 1024); } while (0)
; #define G_MMA(ai, bj, At, Bt) do { __builtin_amdgcn_s_setprio(1); _Pragma("unroll") for (int m = 0; m < 4; ++m) _Pragma("unroll") for (int n = 0; n < 2; ++n) _Pragma("unroll") for (int k = 0; k < 2; ++k) \
;     acc[ai][bj][m][n] = __builtin_amdgcn_mfma_f32_16x16x32_bf16(Bt[n][k], At[m][k], acc[ai][bj][m][n], 0, 0, 0); __builtin_amdgcn_s_setprio(0); } while (0)
; #define G_WAIT_V(n) asm volatile("s_waitcnt vmcnt(" #n ")" ::: "memory")
; #define G_WAIT_L(n) asm volatile("s_waitcnt lgkmcnt(" #n ")" ::: "memory")
; #define G_BAR __builtin_amdgcn_s_barrier()
; #define G_SCHED __builtin_amdgcn_sched_barrier(0)
; template <int GP> DI void gemm_phase(const Params& p, int l, int which, char* smem, int wv) {
;     ...
;       G_WAIT_V(6); G_BAR; G_MMA(1, 1, At, B1); G_BAR;
;       G_LDB(B0, 1, 0); G_SCHED; G_LDA(At, 1, 0); G_STAGE(G_SA(0, 1), a2 + hstep, voffA);
;       G_WAIT_L(8); G_BAR; G_WAIT_L(0); G_MMA(0, 0, At, B0); G_BAR; G_SCHED;
;       G_LDB(B1, 1, 1); G_STAGE(G_SB(1, 0), b3, vb0);
;       G_BAR; G_WAIT_L(0); G_MMA(0, 1, At, B1); G_BAR;
;       G_LDA(At, 1, 1); G_STAGE(G_SA(1, 0), a3, voffA);
;       G_BAR; G_WAIT_L(0); G_MMA(1, 0, At, B0); G_BAR; G_SCHED;
	v_mfma_f32_16x16x32_bf16 v[94:97], v[216:219], v[184:187], v[94:97]
	v_mfma_f32_16x16x32_bf16 v[102:105], v[224:227], v[184:187], v[102:105]
	v_mfma_f32_16x16x32_bf16 v[106:109], v[216:219], v[192:195], v[106:109]
	v_mfma_f32_16x16x32_bf16 v[110:113], v[224:227], v[192:195], v[110:113]
	v_mfma_f32_16x16x32_bf16 v[114:117], v[216:219], v[200:203], v[114:117]
	v_mfma_f32_16x16x32_bf16 v[118:121], v[224:227], v[200:203], v[118:121]
	v_mfma_f32_16x16x32_bf16 v[122:125], v[216:219], v[208:211], v[122:125]
	v_mfma_f32_16x16x32_bf16 v[126:129], v[224:227], v[208:211], v[126:129]
	v_mfma_f32_16x16x32_bf16 v[94:97], v[220:223], v[188:191], v[94:97]
	v_mfma_f32_16x16x32_bf16 v[102:105], v[238:241], v[188:191], v[102:105]
	v_mfma_f32_16x16x32_bf16 v[106:109], v[220:223], v[196:199], v[106:109]
	v_mfma_f32_16x16x32_bf16 v[110:113], v[238:241], v[196:199], v[110:113]
	v_mfma_f32_16x16x32_bf16 v[114:117], v[220:223], v[204:207], v[114:117]
	v_mfma_f32_16x16x32_bf16 v[118:121], v[238:241], v[204:207], v[118:121]
	v_mfma_f32_16x16x32_bf16 v[122:125], v[220:223], v[212:215], v[122:125]
	v_mfma_f32_16x16x32_bf16 v[126:129], v[238:241], v[212:215], v[126:129]
	v_add_u32_e32 v135, 0x18000, v166
	s_barrier
	ds_read_b128 v[168:171], v135
	ds_read_b128 v[172:175], v135 offset:1024
	ds_read_b128 v[176:179], v135 offset:2048
	ds_read_b128 v[180:183], v135 offset:3072
	s_add_u32 s100, s30, 0x80000
	s_addc_u32 s101, s31, 0
	s_mov_b32 m0, s43
	ds_read_b128 v[184:187], v165 offset:32768
	ds_read_b128 v[188:191], v165 offset:33792
	ds_read_b128 v[192:195], v165 offset:34816
	ds_read_b128 v[196:199], v165 offset:35840
	ds_read_b128 v[200:203], v165 offset:36864
	ds_read_b128 v[204:207], v165 offset:37888
	ds_read_b128 v[208:211], v165 offset:38912
	ds_read_b128 v[212:215], v165 offset:39936
	global_load_lds_dwordx4 v130, s[100:101]
	s_mov_b32 m0, s44
	s_nop 0
	global_load_lds_dwordx4 v132, s[100:101]
	s_waitcnt lgkmcnt(8)
	s_barrier
	s_waitcnt lgkmcnt(0)
	v_mfma_f32_16x16x32_bf16 v[62:65], v[168:171], v[184:187], v[62:65]
	v_mfma_f32_16x16x32_bf16 v[58:61], v[176:179], v[184:187], v[58:61]
	v_mfma_f32_16x16x32_bf16 v[54:57], v[168:171], v[192:195], v[54:57]
	v_mfma_f32_16x16x32_bf16 v[50:53], v[176:179], v[192:195], v[50:53]
	v_mfma_f32_16x16x32_bf16 v[46:49], v[168:171], v[200:203], v[46:49]
	v_mfma_f32_16x16x32_bf16 v[42:45], v[176:179], v[200:203], v[42:45]
	v_mfma_f32_16x16x32_bf16 v[38:41], v[168:171], v[208:211], v[38:41]
	v_mfma_f32_16x16x32_bf16 v[34:37], v[176:179], v[208:211], v[34:37]
	v_mfma_f32_16x16x32_bf16 v[62:65], v[172:175], v[188:191], v[62:65]
	v_mfma_f32_16x16x32_bf16 v[58:61], v[180:183], v[188:191], v[58:61]
	v_mfma_f32_16x16x32_bf16 v[54:57], v[172:175], v[196:199], v[54:57]
	v_mfma_f32_16x16x32_bf16 v[50:53], v[180:183], v[196:199], v[50:53]
	v_mfma_f32_16x16x32_bf16 v[46:49], v[172:175], v[204:207], v[46:49]
	v_mfma_f32_16x16x32_bf16 v[42:45], v[180:183], v[204:207], v[42:45]
	v_mfma_f32_16x16x32_bf16 v[38:41], v[172:175], v[212:215], v[38:41]
	v_mfma_f32_16x16x32_bf16 v[34:37], v[180:183], v[212:215], v[34:37]
	s_barrier
	s_mov_b32 m0, s45
	v_add_u32_e32 v135, 0x1c000, v166
	s_add_u32 s100, s28, s74
	s_addc_u32 s101, s29, s75
	ds_read_b128 v[216:219], v135
	ds_read_b128 v[220:223], v135 offset:1024
	ds_read_b128 v[224:227], v135 offset:2048
	ds_read_b128 v[238:241], v135 offset:3072
	global_load_lds_dwordx4 v0, s[100:101]
	s_mov_b32 m0, s46
	s_nop 0
	global_load_lds_dwordx4 v136, s[100:101]
	s_barrier
	s_waitcnt lgkmcnt(0)
	v_mfma_f32_16x16x32_bf16 v[30:33], v[216:219], v[184:187], v[30:33]
	v_mfma_f32_16x16x32_bf16 v[26:29], v[224:227], v[184:187], v[26:29]
	v_mfma_f32_16x16x32_bf16 v[22:25], v[216:219], v[192:195], v[22:25]
	v_mfma_f32_16x16x32_bf16 v[18:21], v[224:227], v[192:195], v[18:21]
	v_mfma_f32_16x16x32_bf16 v[14:17], v[216:219], v[200:203], v[14:17]
	v_mfma_f32_16x16x32_bf16 v[10:13], v[224:227], v[200:203], v[10:13]
	v_mfma_f32_16x16x32_bf16 v[6:9], v[216:219], v[208:211], v[6:9]
	v_mfma_f32_16x16x32_bf16 v[2:5], v[224:227], v[208:211], v[2:5]
	v_mfma_f32_16x16x32_bf16 v[30:33], v[220:223], v[188:191], v[30:33]
	v_mfma_f32_16x16x32_bf16 v[26:29], v[238:241], v[188:191], v[26:29]
	v_mfma_f32_16x16x32_bf16 v[22:25], v[220:223], v[196:199], v[22:25]
	v_mfma_f32_16x16x32_bf16 v[18:21], v[238:241], v[196:199], v[18:21]
	v_mfma_f32_16x16x32_bf16 v[14:17], v[220:223], v[204:207], v[14:17]
	v_mfma_f32_16x16x32_bf16 v[10:13], v[238:241], v[204:207], v[10:13]
	v_mfma_f32_16x16x32_bf16 v[6:9], v[220:223], v[212:215], v[6:9]
	v_mfma_f32_16x16x32_bf16 v[2:5], v[238:241], v[212:215], v[2:5]
	s_mov_b32 m0, s48
	s_add_u32 s100, s30, s74
	s_addc_u32 s101, s31, s75
	s_barrier
; #define G_STAGE(bufoff, gbase, voff) do { _Pragma("unroll") for (int _i = 0; _i < 2; ++_i) \
;     __builtin_amdgcn_global_load_lds((const unsigned*)((const char*)(gbase) + (voff)[_i]), (LAS unsigned*)(lds + (bufoff) + ldsw + _i * 8192), 16, 0, 0); } while (0)
; #define G_LDA(dst, b, h) do { _Pragma("unroll") for (int m = 0; m < 4; ++m) _Pragma("unroll") for (int k = 0; k < 2; ++k) dst[m][k] = *(const LAS bf16x8*)(lds + G_SA(b, h) + aoff + m * 2048 + k * 1024); } while (0)
; #define G_MMA(ai, bj, At, Bt) do { __builtin_amdgcn_s_setprio(1); _Pragma("unroll") for (int m = 0; m < 4; ++m) _Pragma("unroll") for (int n = 0; n < 2; ++n) _Pragma("unroll") for (int k = 0; k < 2; ++k) \
;     acc[ai][bj][m][n] = __builtin_amdgcn_mfma_f32_16x16x32_bf16(Bt[n][k], At[m][k], acc[ai][bj][m][n], 0, 0, 0); __builtin_amdgcn_s_setprio(0); } while (0)
; #define G_WAIT_V(n) asm volatile("s_waitcnt vmcnt(" #n ")" ::: "memory")
; #define G_WAIT_L(n) asm volatile("s_waitcnt lgkmcnt(" #n ")" ::: "memory")
; #define G_BAR __builtin_amdgcn_s_barrier()
; #define G_SCHED __builtin_amdgcn_sched_barrier(0)
; template <int GP> DI void gemm_phase(const Params& p, int l, int which, char* smem, int wv) {
;     ...
;       G_LDA(At, 1, 1); G_STAGE(G_SA(1, 0), a3, voffA);
;       G_BAR; G_WAIT_L(0); G_MMA(1, 0, At, B0); G_BAR; G_SCHED;
;       G_STAGE(G_SB(1, 1), b3, vb1);
;       G_WAIT_V(6); G_BAR; G_MMA(1, 1, At, B1); G_BAR;
;     }
;     if (GP == 0) {
;       const int m0 = cmt * 256, n0 = cnt_ * 256;
;       const bool isctx = (cmt % 9) == 0;
;       const int head = wc >> 1;
;       const int n128 = cnt_ * 2 + head;
;       const int rowl0 = wr * 64 + fr;
;       if (which) {
;         const int colb = n0 + head * 128 + (wc & 1) * 32 + fq * 8;
;         u16* ybase = isctx ? p.ypart + ((size_t)(ck0 >> 8) * 1024 + (size_t)(cmt / 9) * 256) * DM : p.y + (size_t)m0 * DM;
	ds_read_b128 v[184:187], v165 offset:49152
	ds_read_b128 v[188:191], v165 offset:50176
	ds_read_b128 v[192:195], v165 offset:51200
	ds_read_b128 v[196:199], v165 offset:52224
	ds_read_b128 v[200:203], v165 offset:53248
	ds_read_b128 v[204:207], v165 offset:54272
	ds_read_b128 v[208:211], v165 offset:55296
	ds_read_b128 v[212:215], v165 offset:56320
	global_load_lds_dwordx4 v130, s[100:101]
	s_mov_b32 m0, s49
	s_nop 0
	global_load_lds_dwordx4 v132, s[100:101]
	s_barrier
	s_waitcnt lgkmcnt(0)
	v_mfma_f32_16x16x32_bf16 v[66:69], v[168:171], v[184:187], v[66:69]
	v_mfma_f32_16x16x32_bf16 v[70:73], v[176:179], v[184:187], v[70:73]
	v_mfma_f32_16x16x32_bf16 v[74:77], v[168:171], v[192:195], v[74:77]
	v_mfma_f32_16x16x32_bf16 v[78:81], v[176:179], v[192:195], v[78:81]
	v_mfma_f32_16x16x32_bf16 v[82:85], v[168:171], v[200:203], v[82:85]
	v_mfma_f32_16x16x32_bf16 v[86:89], v[176:179], v[200:203], v[86:89]
	v_mfma_f32_16x16x32_bf16 v[90:93], v[168:171], v[208:211], v[90:93]
	v_mfma_f32_16x16x32_bf16 v[98:101], v[176:179], v[208:211], v[98:101]
	v_mfma_f32_16x16x32_bf16 v[66:69], v[172:175], v[188:191], v[66:69]
	v_mfma_f32_16x16x32_bf16 v[70:73], v[180:183], v[188:191], v[70:73]
	v_mfma_f32_16x16x32_bf16 v[74:77], v[172:175], v[196:199], v[74:77]
	v_mfma_f32_16x16x32_bf16 v[78:81], v[180:183], v[196:199], v[78:81]
	v_mfma_f32_16x16x32_bf16 v[82:85], v[172:175], v[204:207], v[82:85]
	v_mfma_f32_16x16x32_bf16 v[86:89], v[180:183], v[204:207], v[86:89]
	v_mfma_f32_16x16x32_bf16 v[90:93], v[172:175], v[212:215], v[90:93]
	v_mfma_f32_16x16x32_bf16 v[98:101], v[180:183], v[212:215], v[98:101]
	s_barrier
	s_mov_b32 m0, s50
	s_add_u32 s100, s28, s74
	s_addc_u32 s101, s29, s75
	global_load_lds_dwordx4 v134, s[100:101]
	s_mov_b32 m0, s52
	s_nop 0
	global_load_lds_dwordx4 v154, s[100:101]
	s_waitcnt vmcnt(6)
	s_barrier
	v_mfma_f32_16x16x32_bf16 v[94:97], v[216:219], v[184:187], v[94:97]
	v_mfma_f32_16x16x32_bf16 v[102:105], v[224:227], v[184:187], v[102:105]
	v_mfma_f32_16x16x32_bf16 v[106:109], v[216:219], v[192:195], v[106:109]
	v_mfma_f32_16x16x32_bf16 v[110:113], v[224:227], v[192:195], v[110:113]
	v_mfma_f32_16x16x32_bf16 v[114:117], v[216:219], v[200:203], v[114:117]
	v_mfma_f32_16x16x32_bf16 v[118:121], v[224:227], v[200:203], v[118:121]
	v_mfma_f32_16x16x32_bf16 v[122:125], v[216:219], v[208:211], v[122:125]
	v_mfma_f32_16x16x32_bf16 v[126:129], v[224:227], v[208:211], v[126:129]
	v_mfma_f32_16x16x32_bf16 v[94:97], v[220:223], v[188:191], v[94:97]
	v_mfma_f32_16x16x32_bf16 v[102:105], v[238:241], v[188:191], v[102:105]
	v_mfma_f32_16x16x32_bf16 v[106:109], v[220:223], v[196:199], v[106:109]
	v_mfma_f32_16x16x32_bf16 v[110:113], v[238:241], v[196:199], v[110:113]
	v_mfma_f32_16x16x32_bf16 v[114:117], v[220:223], v[204:207], v[114:117]
	v_mfma_f32_16x16x32_bf16 v[118:121], v[238:241], v[204:207], v[118:121]
	v_mfma_f32_16x16x32_bf16 v[122:125], v[220:223], v[212:215], v[122:125]
	v_mfma_f32_16x16x32_bf16 v[126:129], v[238:241], v[212:215], v[126:129]
	s_add_i32 s28, s60, 2
	s_add_u32 s26, s26, 0x100
	s_addc_u32 s27, s27, 0
	v_lshl_add_u64 v[162:163], v[162:163], 0, s[78:79]
	s_cmp_ge_i32 s60, s36
	v_lshl_add_u64 v[160:161], v[160:161], 0, s[78:79]
	s_barrier
	s_cbranch_scc0 .LBB0_147
	s_mul_hi_i32 s11, s2, 0x38e38e39
	s_lshr_b32 s26, s11, 31
	s_ashr_i32 s11, s11, 1
	s_add_i32 s26, s11, s26
	s_mul_i32 s11, s26, 9
	s_sub_i32 s11, s2, s11
	s_cmp_lg_u32 s11, 0
	s_cbranch_scc0 .LBB0_155
	s_lshl_b32 s28, s2, 8
	s_ashr_i32 s29, s28, 31
	s_lshl_b64 s[28:29], s[28:29], 12
	s_add_u32 s28, s94, s28
	s_addc_u32 s29, s95, s29
	s_cbranch_execnz .LBB0_153
